# weight-conversion items: S5-chain workgroups take 17 items per wave and the others 13.75 (they now have the longer mixing path)
# baseline (speedup 1.0000x reference)
; #define LAS __attribute__((address_space(3)))
; #define FRESH_IDS() int tid_ = threadIdx.x; asm volatile("" : "+v"(tid_)); const int lane = tid_ & 63; const int gt = bx * (NWAVES * 64) + tid_; (void)lane; (void)gt
; __device__ __forceinline__ void transpose_item(const float* __restrict__ W, int N, bf16* __restrict__ WT, int ld, int koff, int HG, LAS float* scr, int item, int lane) {
;     const int nblk = N / 32, kb = item / nblk, nb = item % nblk, k0 = 64 * kb, n0 = 32 * nb;
;     { f32x4 v[8]; const int kr = lane >> 3, n4 = (lane & 7) * 4;
; #pragma unroll
;       for (int i = 0; i < 8; ++i) v[i] = *(const f32x4*)(W + (size_t)(k0 + kr + 8 * i) * N + n0 + n4);
; #pragma unroll
;       for (int i = 0; i < 8; ++i) { LAS float* d = scr + (kr + 8 * i) * 33 + n4; d[0] = v[i][0]; d[1] = v[i][1]; d[2] = v[i][2]; d[3] = v[i][3]; } }
;     asm volatile("s_waitcnt lgkmcnt(0)" ::: "memory");
;     const int c = lane & 7;
; #pragma unroll
;     for (int j = 0; j < 4; ++j) { const int n = (lane >> 3) + 8 * j; const LAS float* s = scr + (8 * c) * 33 + n;
; __global__ void __launch_bounds__(NWAVES * 64, 2) hybrid_fwd(Args args) {
;     ...
;             if (pass == par) { if (conv_on) { FRESH_IDS();
;             const float* w_inc = args.in[2] + (size_t)lc * DM * INW;
;             LAS float* scr = (LAS float*)(lds + wave * 16384);
;             constexpr int I_IN = (DM / 64) * (INW / 32), I_SB = (SBW / 64) * (DM / 32), I_SS = (SSMW / 64) * (DM / 32), I_MM = (MEMW / 64) * (DM / 32), I_GL = (SSMW / 64) * (1024 / 32),
;                           I_O = (DM / 64) * (DM / 32), I_GU = (DM / 64) * (2 * DFF / 32), I_DN = (DFF / 64) * (DM / 32);
;             constexpr int NITEMS = I_IN + I_SB + I_SS + I_MM + I_GL + I_O + I_GU + I_DN;
;             for (int it = gw; it < NITEMS; it += NGW) {
;                 int r = it; const float* W; bf16* WT; int N, ld, koff = 0, HG = 0;
;                 if (r < I_IN) { W = w_inc; N = INW; WT = NXT(BT_IN); ld = DM; }
.LBB0_442:
	s_and_b64 vcc, exec, s[2:3]
	s_cbranch_vccz .LBB0_568
	v_readlane_b32 s2, v254, 25
	v_readlane_b32 s3, v254, 26
	s_and_b64 vcc, exec, s[2:3]
	s_cbranch_vccz .LBB0_568
	v_readlane_b32 s0, v251, 56
	v_readlane_b32 s1, v251, 57
	s_waitcnt vmcnt(0)
	v_mov_b32_e32 v21, v0
	s_andn2_b64 vcc, exec, s[0:1]
	s_cbranch_vccnz .LBB0_512
	v_bfe_u32 v14, v21, 3, 3
	v_and_b32_e32 v3, 7, v21
	v_readlane_b32 s0, v251, 54
	v_lshlrev_b32_e32 v2, 2, v3
	v_mul_u32_u24_e32 v6, 0x84, v14
	v_lshl_add_u32 v5, v3, 4, s0
	v_lshlrev_b32_e32 v4, 3, v3
	v_mul_u32_u24_e32 v3, 0x420, v3
	v_lshlrev_b32_e32 v7, 2, v14
	v_or_b32_e32 v15, 8, v14
	v_or_b32_e32 v16, 16, v14
	v_or_b32_e32 v17, 24, v14
	v_add3_u32 v18, s0, v3, v7
	v_lshlrev_b32_e32 v98, 2, v2
	v_add_u32_e32 v19, v5, v6
	v_lshlrev_b32_e32 v2, 1, v4
	v_readlane_b32 s10, v249, 41
	s_mov_b32 s100, 0x43ff
	s_cmpk_lt_u32 s10, 0x400
	s_cbranch_scc1 .Lcv_s5share
	s_addk_i32 s10, 0x4000
	s_movk_i32 s100, 0x7aff
.Lcv_s5share:
	s_branch .LBB0_470

; #define LAS __attribute__((address_space(3)))
; __device__ __forceinline__ unsigned cvt_pk_w7(float lo, float hi) { return (rne_w7(lo) >> 16) | rne_w7(hi); }
; __device__ __forceinline__ int gated_row(int n, int H) { const int second = n >= H, f = second ? n - H : n; return (f >> 7) * 256 + ((f >> 5) & 3) * 64 + second * 32 + (f & 31); }
; __device__ __forceinline__ void transpose_item(const float* __restrict__ W, int N, bf16* __restrict__ WT, int ld, int koff, int HG, LAS float* scr, int item, int lane) {
;     ...
;     for (int j = 0; j < 4; ++j) { const int n = (lane >> 3) + 8 * j; const LAS float* s = scr + (8 * c) * 33 + n;
;         u32x4 o; o.x = cvt_pk_w7(s[0 * 33], s[1 * 33]); o.y = cvt_pk_w7(s[2 * 33], s[3 * 33]); o.z = cvt_pk_w7(s[4 * 33], s[5 * 33]); o.w = cvt_pk_w7(s[6 * 33], s[7 * 33]);
;         const int drow = HG ? gated_row(n0 + n, HG) : (n0 + n);
;         *(u32x4*)(WT + (size_t)drow * ld + koff + k0 + 8 * c) = o; }
;     asm volatile("s_waitcnt lgkmcnt(0)" ::: "memory");
; __global__ void __launch_bounds__(NWAVES * 64, 2) hybrid_fwd(Args args) {
;     ...
;             for (int it = gw; it < NITEMS; it += NGW) {
.LBB0_469:
	s_waitcnt lgkmcnt(3)
	v_bfe_u32 v20, v12, 17, 1
	v_add3_u32 v12, v12, v20, s55
	v_bfe_u32 v20, v13, 17, 1
	v_add3_u32 v13, v13, v20, s55
	v_lshrrev_b32_e32 v12, 16, v12
	v_and_b32_e32 v13, 0xfffe0000, v13
	v_and_or_b32 v22, v12, s57, v13
	s_waitcnt lgkmcnt(2)
	v_bfe_u32 v12, v10, 17, 1
	v_add3_u32 v10, v10, v12, s55
	v_bfe_u32 v12, v11, 17, 1
	v_add3_u32 v11, v11, v12, s55
	v_lshrrev_b32_e32 v10, 16, v10
	v_and_b32_e32 v11, 0xfffe0000, v11
	v_and_or_b32 v23, v10, s57, v11
	s_waitcnt lgkmcnt(1)
	v_bfe_u32 v10, v8, 17, 1
	v_add3_u32 v8, v8, v10, s55
	v_bfe_u32 v10, v9, 17, 1
	v_add3_u32 v9, v9, v10, s55
	v_lshrrev_b32_e32 v8, 16, v8
	v_and_b32_e32 v9, 0xfffe0000, v9
	v_and_or_b32 v24, v8, s57, v9
	s_waitcnt lgkmcnt(0)
	v_bfe_u32 v8, v6, 17, 1
	v_add3_u32 v6, v6, v8, s55
	v_bfe_u32 v8, v7, 17, 1
	v_add3_u32 v7, v7, v8, s55
	v_lshrrev_b32_e32 v6, 16, v6
	v_and_b32_e32 v7, 0xfffe0000, v7
	v_and_or_b32 v25, v6, s57, v7
	v_ashrrev_i32_e32 v6, 31, v3
	v_mul_lo_u32 v8, s3, v3
	v_mul_lo_u32 v9, s2, v6
	v_mad_u64_u32 v[6:7], s[0:1], s2, v3, 0
	v_add3_u32 v7, v7, v9, v8
	v_lshl_add_u64 v[4:5], v[6:7], 1, v[4:5]
	global_store_dwordx4 v[4:5], v[22:25], off
	s_waitcnt lgkmcnt(0)
	s_addk_i32 s10, 0x400
	s_cmp_gt_i32 s10, s100
	s_cbranch_scc1 .LBB0_512
